# CIN GELU epilogue: counted vmcnt per row-sum load instead of one vmcnt(0) in front of the eight conversions
# baseline (speedup 1.0000x reference)
; __device__ __forceinline__ unsigned cvt_pk_bf16(float lo, float hi) { unsigned r; asm volatile("v_cvt_pk_bf16_f32 %0, %1, %2" : "=v"(r) : "v"(lo), "v"(hi)); return r; }
; __device__ __forceinline__ float gelu_tanh(float x) { const float u = 0.7978845608028654f * (x + 0.044715f * x * x * x); return x * fast_rcp(1.0f + fast_exp2(-2.0f * LOG2E * u)); }
; __device__ __forceinline__ void load_rstd(float (&rsv)[2][4], const ssq_t* ssq, int row0) {
;     ssq_t t[2][4];
; #pragma unroll
;     for (int ai = 0; ai < 2; ++ai)
; #pragma unroll
;         for (int m = 0; m < 4; ++m) t[ai][m] = ssq[row0 + ai * HALF + m * 16];
; #pragma unroll
;     for (int ai = 0; ai < 2; ++ai)
; #pragma unroll
;         for (int m = 0; m < 4; ++m) rsv[ai][m] = __builtin_amdgcn_rsqf((float)t[ai][m] * (SSQ_INV / 1024.0f) + 1e-6f);
; }
;     __device__ __forceinline__ void operator()(const f32x4 (&acc)[2][2][4][2], const Unit& u, int wr, int wc, int fr, int fq) const {
;         const int row0 = u.pm * BM + wr * 64 + fr, col0 = u.pn * BM + wc * 32 + 8 * fq;
;         float rsv[2][4]; load_rstd(rsv, ssq, row0);
; #pragma unroll
;         for (int ai = 0; ai < 2; ++ai)
; #pragma unroll
;             for (int m = 0; m < 4; ++m) { const int row = row0 + ai * HALF + m * 16; bf16_t* rowp = O + (size_t)row * ldc + col0; const float rs = rsv[ai][m];
; #pragma unroll
;                 for (int bj = 0; bj < 2; ++bj) { f32x4 v0 = acc[ai][bj][m][0] * rs, v1 = acc[ai][bj][m][1] * rs;
;                     if (ACT == 1) {
; #pragma unroll
;                         for (int j = 0; j < 4; ++j) { v0[j] = gelu_tanh(v0[j]); v1[j] = gelu_tanh(v1[j]); } }
;                     u32x4 w; w.x = cvt_pk_bf16(v0[0], v0[1]); w.y = cvt_pk_bf16(v0[2], v0[3]); w.z = cvt_pk_bf16(v1[0], v1[1]); w.w = cvt_pk_bf16(v1[2], v1[3]);
;                     *(u32x4*)(rowp + bj * HALF) = w; } }
.LBB0_334:
	v_lshrrev_b32_e32 v152, 8, v170
	v_and_b32_e32 v154, 15, v170
	v_lshl_add_u32 v152, v152, 6, v154
	s_lshl_b32 s10, s64, 8
	v_add_u32_e32 v152, s10, v152
	v_lshlrev_b32_e32 v142, 3, v152
	v_mov_b32_e32 v143, 0
	v_lshl_add_u64 v[142:143], v[142:143], 0, s[26:27]
	global_load_dwordx2 v[144:145], v[142:143], off
	global_load_dwordx2 v[146:147], v[142:143], off offset:128
	global_load_dwordx2 v[148:149], v[142:143], off offset:256
	global_load_dwordx2 v[150:151], v[142:143], off offset:384
	global_load_dwordx2 v[156:157], v[142:143], off offset:1024
	global_load_dwordx2 v[158:159], v[142:143], off offset:1152
	global_load_dwordx2 v[162:163], v[142:143], off offset:1280
	global_load_dwordx2 v[164:165], v[142:143], off offset:1408
	v_bfe_u32 v154, v170, 6, 2
	v_bfe_u32 v160, v170, 4, 2
	v_lshlrev_b32_e32 v154, 5, v154
	v_lshl_or_b32 v154, v160, 3, v154
	s_lshl_b32 s10, s63, 8
	v_add_u32_e32 v154, s10, v154
	v_mul_lo_u32 v152, v152, s28
	v_add_lshl_u32 v160, v152, v154, 1
	v_mov_b32_e32 v166, 0xc038aa3b
	v_mov_b32_e32 v167, 0xc038aa3b
	s_mov_b32 s98, 0x3d372713
	s_mov_b32 s99, 0x3d372713
	s_mov_b32 s100, 0x3f4c422a
	s_mov_b32 s101, 0x3f4c422a
	s_lshl_b32 s10, s28, 5
	s_mov_b32 s11, 0
	s_waitcnt vmcnt(7)
	v_ffbh_u32_e32 v152, v145
	v_min_u32_e32 v152, 32, v152
	v_lshlrev_b64 v[144:145], v152, v[144:145]
	v_min_u32_e32 v144, 1, v144
	v_or_b32_e32 v144, v145, v144
	v_cvt_f32_u32_e32 v144, v144
	v_sub_u32_e32 v152, 32, v152
	v_ldexp_f32 v144, v144, v152
	v_fmamk_f32 v144, v144, 0x30800000, v223
	v_rsq_f32_e32 v144, v144
	s_waitcnt vmcnt(6)
	v_ffbh_u32_e32 v152, v147
	v_min_u32_e32 v152, 32, v152
	v_lshlrev_b64 v[146:147], v152, v[146:147]
	v_min_u32_e32 v146, 1, v146
	v_or_b32_e32 v146, v147, v146
	v_cvt_f32_u32_e32 v146, v146
	v_sub_u32_e32 v152, 32, v152
	v_ldexp_f32 v146, v146, v152
	v_fmamk_f32 v146, v146, 0x30800000, v223
	v_rsq_f32_e32 v146, v146
	s_waitcnt vmcnt(5)
	v_ffbh_u32_e32 v152, v149
	v_min_u32_e32 v152, 32, v152
	v_lshlrev_b64 v[148:149], v152, v[148:149]
	v_min_u32_e32 v148, 1, v148
	v_or_b32_e32 v148, v149, v148
	v_cvt_f32_u32_e32 v148, v148
	v_sub_u32_e32 v152, 32, v152
	v_ldexp_f32 v148, v148, v152
	v_fmamk_f32 v148, v148, 0x30800000, v223
	v_rsq_f32_e32 v148, v148
	s_waitcnt vmcnt(4)
	v_ffbh_u32_e32 v152, v151
	v_min_u32_e32 v152, 32, v152
	v_lshlrev_b64 v[150:151], v152, v[150:151]
	v_min_u32_e32 v150, 1, v150
	v_or_b32_e32 v150, v151, v150
	v_cvt_f32_u32_e32 v150, v150
	v_sub_u32_e32 v152, 32, v152
	v_ldexp_f32 v150, v150, v152
	v_fmamk_f32 v150, v150, 0x30800000, v223
	v_rsq_f32_e32 v150, v150
	s_waitcnt vmcnt(3)
	v_ffbh_u32_e32 v152, v157
	v_min_u32_e32 v152, 32, v152
	v_lshlrev_b64 v[156:157], v152, v[156:157]
	v_min_u32_e32 v156, 1, v156
	v_or_b32_e32 v156, v157, v156
	v_cvt_f32_u32_e32 v156, v156
	v_sub_u32_e32 v152, 32, v152
	v_ldexp_f32 v156, v156, v152
	v_fmamk_f32 v156, v156, 0x30800000, v223
	v_rsq_f32_e32 v156, v156
	s_waitcnt vmcnt(2)
	v_ffbh_u32_e32 v152, v159
	v_min_u32_e32 v152, 32, v152
	v_lshlrev_b64 v[158:159], v152, v[158:159]
	v_min_u32_e32 v158, 1, v158
	v_or_b32_e32 v158, v159, v158
	v_cvt_f32_u32_e32 v158, v158
	v_sub_u32_e32 v152, 32, v152
	v_ldexp_f32 v158, v158, v152
	v_fmamk_f32 v158, v158, 0x30800000, v223
	v_rsq_f32_e32 v158, v158
	s_waitcnt vmcnt(1)
	v_ffbh_u32_e32 v152, v163
	v_min_u32_e32 v152, 32, v152
	v_lshlrev_b64 v[162:163], v152, v[162:163]
	v_min_u32_e32 v162, 1, v162
	v_or_b32_e32 v162, v163, v162
	v_cvt_f32_u32_e32 v162, v162
	v_sub_u32_e32 v152, 32, v152
	v_ldexp_f32 v162, v162, v152
	v_fmamk_f32 v162, v162, 0x30800000, v223
	v_rsq_f32_e32 v162, v162
	s_waitcnt vmcnt(0)
	v_ffbh_u32_e32 v152, v165
	v_min_u32_e32 v152, 32, v152
	v_lshlrev_b64 v[164:165], v152, v[164:165]
	v_min_u32_e32 v164, 1, v164
	v_or_b32_e32 v164, v165, v164
	v_cvt_f32_u32_e32 v164, v164
	v_sub_u32_e32 v152, 32, v152
	v_ldexp_f32 v164, v164, v152
	v_fmamk_f32 v164, v164, 0x30800000, v223
	v_rsq_f32_e32 v164, v164
	s_nop 1
	v_mov_b32_e32 v165, v164
	v_mov_b32_e32 v164, v162
	v_mov_b32_e32 v163, v158
	v_mov_b32_e32 v162, v156
	v_mov_b32_e32 v159, v150
	v_mov_b32_e32 v158, v148
	v_mov_b32_e32 v157, v146
	v_mov_b32_e32 v156, v144
	v_mov_b32_e32 v142, v160
	v_mov_b32_e32 v143, 0
	v_lshl_add_u64 v[142:143], v[142:143], 0, s[30:31]
	v_pk_mul_f32 v[120:121], v[120:121], v[156:157] op_sel_hi:[1,0]
	v_pk_mul_f32 v[122:123], v[122:123], v[156:157] op_sel_hi:[1,0]
	v_pk_mul_f32 v[124:125], v[124:125], v[156:157] op_sel_hi:[1,0]
	v_pk_mul_f32 v[126:127], v[126:127], v[156:157] op_sel_hi:[1,0]
	v_pk_mul_f32 v[144:145], v[120:121], s[98:99]
	v_pk_mul_f32 v[146:147], v[122:123], s[98:99]
	v_pk_mul_f32 v[148:149], v[124:125], s[98:99]
	v_pk_mul_f32 v[150:151], v[126:127], s[98:99]
	v_pk_mul_f32 v[144:145], v[120:121], v[144:145]
	v_pk_mul_f32 v[146:147], v[122:123], v[146:147]
	v_pk_mul_f32 v[148:149], v[124:125], v[148:149]
	v_pk_mul_f32 v[150:151], v[126:127], v[150:151]
	v_pk_fma_f32 v[144:145], v[120:121], v[144:145], v[120:121]
	v_pk_fma_f32 v[146:147], v[122:123], v[146:147], v[122:123]
	v_pk_fma_f32 v[148:149], v[124:125], v[148:149], v[124:125]
	v_pk_fma_f32 v[150:151], v[126:127], v[150:151], v[126:127]
	v_pk_mul_f32 v[144:145], v[144:145], s[100:101]
	v_pk_mul_f32 v[146:147], v[146:147], s[100:101]
	v_pk_mul_f32 v[148:149], v[148:149], s[100:101]
	v_pk_mul_f32 v[150:151], v[150:151], s[100:101]
	v_pk_mul_f32 v[144:145], v[144:145], v[166:167]
	v_pk_mul_f32 v[146:147], v[146:147], v[166:167]
	v_pk_mul_f32 v[148:149], v[148:149], v[166:167]
	v_pk_mul_f32 v[150:151], v[150:151], v[166:167]
	v_exp_f32_e32 v144, v144
	v_exp_f32_e32 v145, v145
	v_exp_f32_e32 v146, v146
	v_exp_f32_e32 v147, v147
	v_exp_f32_e32 v148, v148
; __device__ __forceinline__ unsigned cvt_pk_bf16(float lo, float hi) { unsigned r; asm volatile("v_cvt_pk_bf16_f32 %0, %1, %2" : "=v"(r) : "v"(lo), "v"(hi)); return r; }
; __device__ __forceinline__ float fast_exp2(float x) { return __builtin_amdgcn_exp2f(x); }
; __device__ __forceinline__ float fast_rcp(float x) { return __builtin_amdgcn_rcpf(x); }
; __device__ __forceinline__ float gelu_tanh(float x) { const float u = 0.7978845608028654f * (x + 0.044715f * x * x * x); return x * fast_rcp(1.0f + fast_exp2(-2.0f * LOG2E * u)); }
; __device__ __forceinline__ float sigmoidf_(float x) { return fast_rcp(1.0f + fast_exp2(-LOG2E * x)); }
; __device__ __forceinline__ float siluf_(float x) { return x * sigmoidf_(x); }
;     __device__ __forceinline__ void operator()(const f32x4 (&acc)[2][2][4][2], const Unit& u, int wr, int wc, int fr, int fq) const {
;     ...
;             for (int m = 0; m < 4; ++m) { const int row = row0 + ai * HALF + m * 16; bf16_t* rowp = O + (size_t)row * ldc + col0; const float rs = rsv[ai][m];
; #pragma unroll
;                 for (int bj = 0; bj < 2; ++bj) { f32x4 v0 = acc[ai][bj][m][0] * rs, v1 = acc[ai][bj][m][1] * rs;
;                     if (ACT == 1) {
; #pragma unroll
;                         for (int j = 0; j < 4; ++j) { v0[j] = gelu_tanh(v0[j]); v1[j] = gelu_tanh(v1[j]); } }
;                     u32x4 w; w.x = cvt_pk_bf16(v0[0], v0[1]); w.y = cvt_pk_bf16(v0[2], v0[3]); w.z = cvt_pk_bf16(v1[0], v1[1]); w.w = cvt_pk_bf16(v1[2], v1[3]);
;                     *(u32x4*)(rowp + bj * HALF) = w; } }
	v_exp_f32_e32 v149, v149
	v_exp_f32_e32 v150, v150
	v_exp_f32_e32 v151, v151
	v_add_f32_e32 v144, 1.0, v144
	v_add_f32_e32 v145, 1.0, v145
	v_add_f32_e32 v146, 1.0, v146
	v_add_f32_e32 v147, 1.0, v147
	v_add_f32_e32 v148, 1.0, v148
	v_add_f32_e32 v149, 1.0, v149
	v_add_f32_e32 v150, 1.0, v150
	v_add_f32_e32 v151, 1.0, v151
	v_rcp_f32_e32 v144, v144
	v_rcp_f32_e32 v145, v145
	v_rcp_f32_e32 v146, v146
	v_rcp_f32_e32 v147, v147
	v_rcp_f32_e32 v148, v148
	v_rcp_f32_e32 v149, v149
	v_rcp_f32_e32 v150, v150
	v_rcp_f32_e32 v151, v151
	v_nop
	v_pk_mul_f32 v[120:121], v[120:121], v[144:145]
	v_pk_mul_f32 v[122:123], v[122:123], v[146:147]
	v_pk_mul_f32 v[124:125], v[124:125], v[148:149]
	v_pk_mul_f32 v[126:127], v[126:127], v[150:151]
	v_cvt_pk_bf16_f32 v120, v120, v121
	v_cvt_pk_bf16_f32 v121, v122, v123
	v_cvt_pk_bf16_f32 v122, v124, v125
	v_cvt_pk_bf16_f32 v123, v126, v127
	global_store_dwordx4 v[142:143], v[120:123], off
	v_pk_mul_f32 v[116:117], v[116:117], v[156:157] op_sel_hi:[1,0]
	v_pk_mul_f32 v[118:119], v[118:119], v[156:157] op_sel_hi:[1,0]
	v_pk_mul_f32 v[112:113], v[112:113], v[156:157] op_sel_hi:[1,0]
	v_pk_mul_f32 v[114:115], v[114:115], v[156:157] op_sel_hi:[1,0]
	v_pk_mul_f32 v[144:145], v[116:117], s[98:99]
	v_pk_mul_f32 v[146:147], v[118:119], s[98:99]
	v_pk_mul_f32 v[148:149], v[112:113], s[98:99]
	v_pk_mul_f32 v[150:151], v[114:115], s[98:99]
	v_pk_mul_f32 v[144:145], v[116:117], v[144:145]
	v_pk_mul_f32 v[146:147], v[118:119], v[146:147]
	v_pk_mul_f32 v[148:149], v[112:113], v[148:149]
	v_pk_mul_f32 v[150:151], v[114:115], v[150:151]
	v_pk_fma_f32 v[144:145], v[116:117], v[144:145], v[116:117]
	v_pk_fma_f32 v[146:147], v[118:119], v[146:147], v[118:119]
	v_pk_fma_f32 v[148:149], v[112:113], v[148:149], v[112:113]
	v_pk_fma_f32 v[150:151], v[114:115], v[150:151], v[114:115]
	v_pk_mul_f32 v[144:145], v[144:145], s[100:101]
	v_pk_mul_f32 v[146:147], v[146:147], s[100:101]
	v_pk_mul_f32 v[148:149], v[148:149], s[100:101]
	v_pk_mul_f32 v[150:151], v[150:151], s[100:101]
	v_pk_mul_f32 v[144:145], v[144:145], v[166:167]
	v_pk_mul_f32 v[146:147], v[146:147], v[166:167]
	v_pk_mul_f32 v[148:149], v[148:149], v[166:167]
	v_pk_mul_f32 v[150:151], v[150:151], v[166:167]
	v_exp_f32_e32 v144, v144
	v_exp_f32_e32 v145, v145
	v_exp_f32_e32 v146, v146
	v_exp_f32_e32 v147, v147
	v_exp_f32_e32 v148, v148
	v_exp_f32_e32 v149, v149
	v_exp_f32_e32 v150, v150
	v_exp_f32_e32 v151, v151
	v_add_f32_e32 v144, 1.0, v144
	v_add_f32_e32 v145, 1.0, v145
	v_add_f32_e32 v146, 1.0, v146
	v_add_f32_e32 v147, 1.0, v147
	v_add_f32_e32 v148, 1.0, v148
	v_add_f32_e32 v149, 1.0, v149
	v_add_f32_e32 v150, 1.0, v150
	v_add_f32_e32 v151, 1.0, v151
	v_rcp_f32_e32 v144, v144
	v_rcp_f32_e32 v145, v145
	v_rcp_f32_e32 v146, v146
	v_rcp_f32_e32 v147, v147
	v_rcp_f32_e32 v148, v148
	v_rcp_f32_e32 v149, v149
	v_rcp_f32_e32 v150, v150
	v_rcp_f32_e32 v151, v151
	v_nop
	v_pk_mul_f32 v[116:117], v[116:117], v[144:145]
	v_pk_mul_f32 v[118:119], v[118:119], v[146:147]
	v_pk_mul_f32 v[112:113], v[112:113], v[148:149]
	v_pk_mul_f32 v[114:115], v[114:115], v[150:151]
	v_cvt_pk_bf16_f32 v116, v116, v117
	v_cvt_pk_bf16_f32 v117, v118, v119
	v_cvt_pk_bf16_f32 v118, v112, v113
	v_cvt_pk_bf16_f32 v119, v114, v115
	global_store_dwordx4 v[142:143], v[116:119], off offset:256
	v_lshl_add_u64 v[142:143], v[142:143], 0, s[10:11]
	v_pk_mul_f32 v[108:109], v[108:109], v[156:157] op_sel:[0,1]
	v_pk_mul_f32 v[110:111], v[110:111], v[156:157] op_sel:[0,1]
	v_pk_mul_f32 v[104:105], v[104:105], v[156:157] op_sel:[0,1]
	v_pk_mul_f32 v[106:107], v[106:107], v[156:157] op_sel:[0,1]
	v_pk_mul_f32 v[144:145], v[108:109], s[98:99]
	v_pk_mul_f32 v[146:147], v[110:111], s[98:99]
	v_pk_mul_f32 v[148:149], v[104:105], s[98:99]
	v_pk_mul_f32 v[150:151], v[106:107], s[98:99]
	v_pk_mul_f32 v[144:145], v[108:109], v[144:145]
	v_pk_mul_f32 v[146:147], v[110:111], v[146:147]
	v_pk_mul_f32 v[148:149], v[104:105], v[148:149]
	v_pk_mul_f32 v[150:151], v[106:107], v[150:151]
	v_pk_fma_f32 v[144:145], v[108:109], v[144:145], v[108:109]
	v_pk_fma_f32 v[146:147], v[110:111], v[146:147], v[110:111]
	v_pk_fma_f32 v[148:149], v[104:105], v[148:149], v[104:105]
	v_pk_fma_f32 v[150:151], v[106:107], v[150:151], v[106:107]
	v_pk_mul_f32 v[144:145], v[144:145], s[100:101]
	v_pk_mul_f32 v[146:147], v[146:147], s[100:101]
	v_pk_mul_f32 v[148:149], v[148:149], s[100:101]
	v_pk_mul_f32 v[150:151], v[150:151], s[100:101]
	v_pk_mul_f32 v[144:145], v[144:145], v[166:167]
	v_pk_mul_f32 v[146:147], v[146:147], v[166:167]
	v_pk_mul_f32 v[148:149], v[148:149], v[166:167]
	v_pk_mul_f32 v[150:151], v[150:151], v[166:167]
	v_exp_f32_e32 v144, v144
	v_exp_f32_e32 v145, v145
	v_exp_f32_e32 v146, v146
	v_exp_f32_e32 v147, v147
	v_exp_f32_e32 v148, v148
	v_exp_f32_e32 v149, v149
	v_exp_f32_e32 v150, v150
	v_exp_f32_e32 v151, v151
	v_add_f32_e32 v144, 1.0, v144
	v_add_f32_e32 v145, 1.0, v145
	v_add_f32_e32 v146, 1.0, v146
	v_add_f32_e32 v147, 1.0, v147
	v_add_f32_e32 v148, 1.0, v148
	v_add_f32_e32 v149, 1.0, v149
	v_add_f32_e32 v150, 1.0, v150
	v_add_f32_e32 v151, 1.0, v151
	v_rcp_f32_e32 v144, v144
	v_rcp_f32_e32 v145, v145
	v_rcp_f32_e32 v146, v146
	v_rcp_f32_e32 v147, v147
	v_rcp_f32_e32 v148, v148
	v_rcp_f32_e32 v149, v149
	v_rcp_f32_e32 v150, v150
	v_rcp_f32_e32 v151, v151
	v_nop
	v_pk_mul_f32 v[108:109], v[108:109], v[144:145]
	v_pk_mul_f32 v[110:111], v[110:111], v[146:147]
	v_pk_mul_f32 v[104:105], v[104:105], v[148:149]
	v_pk_mul_f32 v[106:107], v[106:107], v[150:151]
	v_cvt_pk_bf16_f32 v108, v108, v109
	v_cvt_pk_bf16_f32 v109, v110, v111
	v_cvt_pk_bf16_f32 v110, v104, v105
	v_cvt_pk_bf16_f32 v111, v106, v107
	global_store_dwordx4 v[142:143], v[108:111], off
; __device__ __forceinline__ unsigned cvt_pk_bf16(float lo, float hi) { unsigned r; asm volatile("v_cvt_pk_bf16_f32 %0, %1, %2" : "=v"(r) : "v"(lo), "v"(hi)); return r; }
; __device__ __forceinline__ float gelu_tanh(float x) { const float u = 0.7978845608028654f * (x + 0.044715f * x * x * x); return x * fast_rcp(1.0f + fast_exp2(-2.0f * LOG2E * u)); }
;     __device__ __forceinline__ void operator()(const f32x4 (&acc)[2][2][4][2], const Unit& u, int wr, int wc, int fr, int fq) const {
;     ...
;             for (int m = 0; m < 4; ++m) { const int row = row0 + ai * HALF + m * 16; bf16_t* rowp = O + (size_t)row * ldc + col0; const float rs = rsv[ai][m];
; #pragma unroll
;                 for (int bj = 0; bj < 2; ++bj) { f32x4 v0 = acc[ai][bj][m][0] * rs, v1 = acc[ai][bj][m][1] * rs;
;                     if (ACT == 1) {
; #pragma unroll
;                         for (int j = 0; j < 4; ++j) { v0[j] = gelu_tanh(v0[j]); v1[j] = gelu_tanh(v1[j]); } }
;                     u32x4 w; w.x = cvt_pk_bf16(v0[0], v0[1]); w.y = cvt_pk_bf16(v0[2], v0[3]); w.z = cvt_pk_bf16(v1[0], v1[1]); w.w = cvt_pk_bf16(v1[2], v1[3]);
;                     *(u32x4*)(rowp + bj * HALF) = w; } }
	v_pk_mul_f32 v[100:101], v[100:101], v[156:157] op_sel:[0,1]
	v_pk_mul_f32 v[102:103], v[102:103], v[156:157] op_sel:[0,1]
	v_pk_mul_f32 v[96:97], v[96:97], v[156:157] op_sel:[0,1]
	v_pk_mul_f32 v[98:99], v[98:99], v[156:157] op_sel:[0,1]
	v_pk_mul_f32 v[144:145], v[100:101], s[98:99]
	v_pk_mul_f32 v[146:147], v[102:103], s[98:99]
	v_pk_mul_f32 v[148:149], v[96:97], s[98:99]
	v_pk_mul_f32 v[150:151], v[98:99], s[98:99]
	v_pk_mul_f32 v[144:145], v[100:101], v[144:145]
	v_pk_mul_f32 v[146:147], v[102:103], v[146:147]
	v_pk_mul_f32 v[148:149], v[96:97], v[148:149]
	v_pk_mul_f32 v[150:151], v[98:99], v[150:151]
	v_pk_fma_f32 v[144:145], v[100:101], v[144:145], v[100:101]
	v_pk_fma_f32 v[146:147], v[102:103], v[146:147], v[102:103]
	v_pk_fma_f32 v[148:149], v[96:97], v[148:149], v[96:97]
	v_pk_fma_f32 v[150:151], v[98:99], v[150:151], v[98:99]
	v_pk_mul_f32 v[144:145], v[144:145], s[100:101]
	v_pk_mul_f32 v[146:147], v[146:147], s[100:101]
	v_pk_mul_f32 v[148:149], v[148:149], s[100:101]
	v_pk_mul_f32 v[150:151], v[150:151], s[100:101]
	v_pk_mul_f32 v[144:145], v[144:145], v[166:167]
	v_pk_mul_f32 v[146:147], v[146:147], v[166:167]
	v_pk_mul_f32 v[148:149], v[148:149], v[166:167]
	v_pk_mul_f32 v[150:151], v[150:151], v[166:167]
	v_exp_f32_e32 v144, v144
	v_exp_f32_e32 v145, v145
	v_exp_f32_e32 v146, v146
	v_exp_f32_e32 v147, v147
	v_exp_f32_e32 v148, v148
	v_exp_f32_e32 v149, v149
	v_exp_f32_e32 v150, v150
	v_exp_f32_e32 v151, v151
	v_add_f32_e32 v144, 1.0, v144
	v_add_f32_e32 v145, 1.0, v145
	v_add_f32_e32 v146, 1.0, v146
	v_add_f32_e32 v147, 1.0, v147
	v_add_f32_e32 v148, 1.0, v148
	v_add_f32_e32 v149, 1.0, v149
	v_add_f32_e32 v150, 1.0, v150
	v_add_f32_e32 v151, 1.0, v151
	v_rcp_f32_e32 v144, v144
	v_rcp_f32_e32 v145, v145
	v_rcp_f32_e32 v146, v146
	v_rcp_f32_e32 v147, v147
	v_rcp_f32_e32 v148, v148
	v_rcp_f32_e32 v149, v149
	v_rcp_f32_e32 v150, v150
	v_rcp_f32_e32 v151, v151
	v_nop
	v_pk_mul_f32 v[100:101], v[100:101], v[144:145]
	v_pk_mul_f32 v[102:103], v[102:103], v[146:147]
	v_pk_mul_f32 v[96:97], v[96:97], v[148:149]
	v_pk_mul_f32 v[98:99], v[98:99], v[150:151]
	v_cvt_pk_bf16_f32 v100, v100, v101
	v_cvt_pk_bf16_f32 v101, v102, v103
	v_cvt_pk_bf16_f32 v102, v96, v97
	v_cvt_pk_bf16_f32 v103, v98, v99
	global_store_dwordx4 v[142:143], v[100:103], off offset:256
	v_lshl_add_u64 v[142:143], v[142:143], 0, s[10:11]
	v_pk_mul_f32 v[92:93], v[92:93], v[158:159] op_sel_hi:[1,0]
	v_pk_mul_f32 v[94:95], v[94:95], v[158:159] op_sel_hi:[1,0]
	v_pk_mul_f32 v[88:89], v[88:89], v[158:159] op_sel_hi:[1,0]
	v_pk_mul_f32 v[90:91], v[90:91], v[158:159] op_sel_hi:[1,0]
	v_pk_mul_f32 v[144:145], v[92:93], s[98:99]
	v_pk_mul_f32 v[146:147], v[94:95], s[98:99]
	v_pk_mul_f32 v[148:149], v[88:89], s[98:99]
	v_pk_mul_f32 v[150:151], v[90:91], s[98:99]
	v_pk_mul_f32 v[144:145], v[92:93], v[144:145]
	v_pk_mul_f32 v[146:147], v[94:95], v[146:147]
	v_pk_mul_f32 v[148:149], v[88:89], v[148:149]
	v_pk_mul_f32 v[150:151], v[90:91], v[150:151]
	v_pk_fma_f32 v[144:145], v[92:93], v[144:145], v[92:93]
	v_pk_fma_f32 v[146:147], v[94:95], v[146:147], v[94:95]
	v_pk_fma_f32 v[148:149], v[88:89], v[148:149], v[88:89]
	v_pk_fma_f32 v[150:151], v[90:91], v[150:151], v[90:91]
	v_pk_mul_f32 v[144:145], v[144:145], s[100:101]
	v_pk_mul_f32 v[146:147], v[146:147], s[100:101]
	v_pk_mul_f32 v[148:149], v[148:149], s[100:101]
	v_pk_mul_f32 v[150:151], v[150:151], s[100:101]
	v_pk_mul_f32 v[144:145], v[144:145], v[166:167]
	v_pk_mul_f32 v[146:147], v[146:147], v[166:167]
	v_pk_mul_f32 v[148:149], v[148:149], v[166:167]
	v_pk_mul_f32 v[150:151], v[150:151], v[166:167]
	v_exp_f32_e32 v144, v144
	v_exp_f32_e32 v145, v145
	v_exp_f32_e32 v146, v146
	v_exp_f32_e32 v147, v147
	v_exp_f32_e32 v148, v148
	v_exp_f32_e32 v149, v149
	v_exp_f32_e32 v150, v150
	v_exp_f32_e32 v151, v151
	v_add_f32_e32 v144, 1.0, v144
	v_add_f32_e32 v145, 1.0, v145
	v_add_f32_e32 v146, 1.0, v146
	v_add_f32_e32 v147, 1.0, v147
	v_add_f32_e32 v148, 1.0, v148
	v_add_f32_e32 v149, 1.0, v149
	v_add_f32_e32 v150, 1.0, v150
	v_add_f32_e32 v151, 1.0, v151
	v_rcp_f32_e32 v144, v144
	v_rcp_f32_e32 v145, v145
	v_rcp_f32_e32 v146, v146
	v_rcp_f32_e32 v147, v147
	v_rcp_f32_e32 v148, v148
	v_rcp_f32_e32 v149, v149
	v_rcp_f32_e32 v150, v150
	v_rcp_f32_e32 v151, v151
	v_nop
	v_pk_mul_f32 v[92:93], v[92:93], v[144:145]
	v_pk_mul_f32 v[94:95], v[94:95], v[146:147]
	v_pk_mul_f32 v[88:89], v[88:89], v[148:149]
	v_pk_mul_f32 v[90:91], v[90:91], v[150:151]
	v_cvt_pk_bf16_f32 v92, v92, v93
	v_cvt_pk_bf16_f32 v93, v94, v95
	v_cvt_pk_bf16_f32 v94, v88, v89
	v_cvt_pk_bf16_f32 v95, v90, v91
	global_store_dwordx4 v[142:143], v[92:95], off
	v_pk_mul_f32 v[84:85], v[84:85], v[158:159] op_sel_hi:[1,0]
	v_pk_mul_f32 v[86:87], v[86:87], v[158:159] op_sel_hi:[1,0]
	v_pk_mul_f32 v[80:81], v[80:81], v[158:159] op_sel_hi:[1,0]
	v_pk_mul_f32 v[82:83], v[82:83], v[158:159] op_sel_hi:[1,0]
	v_pk_mul_f32 v[144:145], v[84:85], s[98:99]
	v_pk_mul_f32 v[146:147], v[86:87], s[98:99]
	v_pk_mul_f32 v[148:149], v[80:81], s[98:99]
	v_pk_mul_f32 v[150:151], v[82:83], s[98:99]
	v_pk_mul_f32 v[144:145], v[84:85], v[144:145]
	v_pk_mul_f32 v[146:147], v[86:87], v[146:147]
	v_pk_mul_f32 v[148:149], v[80:81], v[148:149]
	v_pk_mul_f32 v[150:151], v[82:83], v[150:151]
	v_pk_fma_f32 v[144:145], v[84:85], v[144:145], v[84:85]
	v_pk_fma_f32 v[146:147], v[86:87], v[146:147], v[86:87]
	v_pk_fma_f32 v[148:149], v[80:81], v[148:149], v[80:81]
	v_pk_fma_f32 v[150:151], v[82:83], v[150:151], v[82:83]
	v_pk_mul_f32 v[144:145], v[144:145], s[100:101]
	v_pk_mul_f32 v[146:147], v[146:147], s[100:101]
	v_pk_mul_f32 v[148:149], v[148:149], s[100:101]
	v_pk_mul_f32 v[150:151], v[150:151], s[100:101]
; __device__ __forceinline__ unsigned cvt_pk_bf16(float lo, float hi) { unsigned r; asm volatile("v_cvt_pk_bf16_f32 %0, %1, %2" : "=v"(r) : "v"(lo), "v"(hi)); return r; }
; __device__ __forceinline__ float gelu_tanh(float x) { const float u = 0.7978845608028654f * (x + 0.044715f * x * x * x); return x * fast_rcp(1.0f + fast_exp2(-2.0f * LOG2E * u)); }
;     __device__ __forceinline__ void operator()(const f32x4 (&acc)[2][2][4][2], const Unit& u, int wr, int wc, int fr, int fq) const {
;     ...
;             for (int m = 0; m < 4; ++m) { const int row = row0 + ai * HALF + m * 16; bf16_t* rowp = O + (size_t)row * ldc + col0; const float rs = rsv[ai][m];
; #pragma unroll
;                 for (int bj = 0; bj < 2; ++bj) { f32x4 v0 = acc[ai][bj][m][0] * rs, v1 = acc[ai][bj][m][1] * rs;
;                     if (ACT == 1) {
; #pragma unroll
;                         for (int j = 0; j < 4; ++j) { v0[j] = gelu_tanh(v0[j]); v1[j] = gelu_tanh(v1[j]); } }
;                     u32x4 w; w.x = cvt_pk_bf16(v0[0], v0[1]); w.y = cvt_pk_bf16(v0[2], v0[3]); w.z = cvt_pk_bf16(v1[0], v1[1]); w.w = cvt_pk_bf16(v1[2], v1[3]);
;                     *(u32x4*)(rowp + bj * HALF) = w; } }
	v_pk_mul_f32 v[144:145], v[144:145], v[166:167]
	v_pk_mul_f32 v[146:147], v[146:147], v[166:167]
	v_pk_mul_f32 v[148:149], v[148:149], v[166:167]
	v_pk_mul_f32 v[150:151], v[150:151], v[166:167]
	v_exp_f32_e32 v144, v144
	v_exp_f32_e32 v145, v145
	v_exp_f32_e32 v146, v146
	v_exp_f32_e32 v147, v147
	v_exp_f32_e32 v148, v148
	v_exp_f32_e32 v149, v149
	v_exp_f32_e32 v150, v150
	v_exp_f32_e32 v151, v151
	v_add_f32_e32 v144, 1.0, v144
	v_add_f32_e32 v145, 1.0, v145
	v_add_f32_e32 v146, 1.0, v146
	v_add_f32_e32 v147, 1.0, v147
	v_add_f32_e32 v148, 1.0, v148
	v_add_f32_e32 v149, 1.0, v149
	v_add_f32_e32 v150, 1.0, v150
	v_add_f32_e32 v151, 1.0, v151
	v_rcp_f32_e32 v144, v144
	v_rcp_f32_e32 v145, v145
	v_rcp_f32_e32 v146, v146
	v_rcp_f32_e32 v147, v147
	v_rcp_f32_e32 v148, v148
	v_rcp_f32_e32 v149, v149
	v_rcp_f32_e32 v150, v150
	v_rcp_f32_e32 v151, v151
	v_nop
	v_pk_mul_f32 v[84:85], v[84:85], v[144:145]
	v_pk_mul_f32 v[86:87], v[86:87], v[146:147]
	v_pk_mul_f32 v[80:81], v[80:81], v[148:149]
	v_pk_mul_f32 v[82:83], v[82:83], v[150:151]
	v_cvt_pk_bf16_f32 v84, v84, v85
	v_cvt_pk_bf16_f32 v85, v86, v87
	v_cvt_pk_bf16_f32 v86, v80, v81
	v_cvt_pk_bf16_f32 v87, v82, v83
	global_store_dwordx4 v[142:143], v[84:87], off offset:256
	v_lshl_add_u64 v[142:143], v[142:143], 0, s[10:11]
	v_pk_mul_f32 v[76:77], v[76:77], v[158:159] op_sel:[0,1]
	v_pk_mul_f32 v[78:79], v[78:79], v[158:159] op_sel:[0,1]
	v_pk_mul_f32 v[72:73], v[72:73], v[158:159] op_sel:[0,1]
	v_pk_mul_f32 v[74:75], v[74:75], v[158:159] op_sel:[0,1]
	v_pk_mul_f32 v[144:145], v[76:77], s[98:99]
	v_pk_mul_f32 v[146:147], v[78:79], s[98:99]
	v_pk_mul_f32 v[148:149], v[72:73], s[98:99]
	v_pk_mul_f32 v[150:151], v[74:75], s[98:99]
	v_pk_mul_f32 v[144:145], v[76:77], v[144:145]
	v_pk_mul_f32 v[146:147], v[78:79], v[146:147]
	v_pk_mul_f32 v[148:149], v[72:73], v[148:149]
	v_pk_mul_f32 v[150:151], v[74:75], v[150:151]
	v_pk_fma_f32 v[144:145], v[76:77], v[144:145], v[76:77]
	v_pk_fma_f32 v[146:147], v[78:79], v[146:147], v[78:79]
	v_pk_fma_f32 v[148:149], v[72:73], v[148:149], v[72:73]
	v_pk_fma_f32 v[150:151], v[74:75], v[150:151], v[74:75]
	v_pk_mul_f32 v[144:145], v[144:145], s[100:101]
	v_pk_mul_f32 v[146:147], v[146:147], s[100:101]
	v_pk_mul_f32 v[148:149], v[148:149], s[100:101]
	v_pk_mul_f32 v[150:151], v[150:151], s[100:101]
	v_pk_mul_f32 v[144:145], v[144:145], v[166:167]
	v_pk_mul_f32 v[146:147], v[146:147], v[166:167]
	v_pk_mul_f32 v[148:149], v[148:149], v[166:167]
	v_pk_mul_f32 v[150:151], v[150:151], v[166:167]
	v_exp_f32_e32 v144, v144
	v_exp_f32_e32 v145, v145
	v_exp_f32_e32 v146, v146
	v_exp_f32_e32 v147, v147
	v_exp_f32_e32 v148, v148
	v_exp_f32_e32 v149, v149
	v_exp_f32_e32 v150, v150
	v_exp_f32_e32 v151, v151
	v_add_f32_e32 v144, 1.0, v144
	v_add_f32_e32 v145, 1.0, v145
	v_add_f32_e32 v146, 1.0, v146
	v_add_f32_e32 v147, 1.0, v147
	v_add_f32_e32 v148, 1.0, v148
	v_add_f32_e32 v149, 1.0, v149
	v_add_f32_e32 v150, 1.0, v150
	v_add_f32_e32 v151, 1.0, v151
	v_rcp_f32_e32 v144, v144
	v_rcp_f32_e32 v145, v145
	v_rcp_f32_e32 v146, v146
	v_rcp_f32_e32 v147, v147
	v_rcp_f32_e32 v148, v148
	v_rcp_f32_e32 v149, v149
	v_rcp_f32_e32 v150, v150
	v_rcp_f32_e32 v151, v151
	v_nop
	v_pk_mul_f32 v[76:77], v[76:77], v[144:145]
	v_pk_mul_f32 v[78:79], v[78:79], v[146:147]
	v_pk_mul_f32 v[72:73], v[72:73], v[148:149]
	v_pk_mul_f32 v[74:75], v[74:75], v[150:151]
	v_cvt_pk_bf16_f32 v76, v76, v77
	v_cvt_pk_bf16_f32 v77, v78, v79
	v_cvt_pk_bf16_f32 v78, v72, v73
	v_cvt_pk_bf16_f32 v79, v74, v75
	global_store_dwordx4 v[142:143], v[76:79], off
	v_pk_mul_f32 v[68:69], v[68:69], v[158:159] op_sel:[0,1]
	v_pk_mul_f32 v[70:71], v[70:71], v[158:159] op_sel:[0,1]
	v_pk_mul_f32 v[64:65], v[64:65], v[158:159] op_sel:[0,1]
	v_pk_mul_f32 v[66:67], v[66:67], v[158:159] op_sel:[0,1]
	v_pk_mul_f32 v[144:145], v[68:69], s[98:99]
	v_pk_mul_f32 v[146:147], v[70:71], s[98:99]
	v_pk_mul_f32 v[148:149], v[64:65], s[98:99]
	v_pk_mul_f32 v[150:151], v[66:67], s[98:99]
	v_pk_mul_f32 v[144:145], v[68:69], v[144:145]
	v_pk_mul_f32 v[146:147], v[70:71], v[146:147]
	v_pk_mul_f32 v[148:149], v[64:65], v[148:149]
	v_pk_mul_f32 v[150:151], v[66:67], v[150:151]
	v_pk_fma_f32 v[144:145], v[68:69], v[144:145], v[68:69]
	v_pk_fma_f32 v[146:147], v[70:71], v[146:147], v[70:71]
	v_pk_fma_f32 v[148:149], v[64:65], v[148:149], v[64:65]
	v_pk_fma_f32 v[150:151], v[66:67], v[150:151], v[66:67]
	v_pk_mul_f32 v[144:145], v[144:145], s[100:101]
	v_pk_mul_f32 v[146:147], v[146:147], s[100:101]
	v_pk_mul_f32 v[148:149], v[148:149], s[100:101]
	v_pk_mul_f32 v[150:151], v[150:151], s[100:101]
	v_pk_mul_f32 v[144:145], v[144:145], v[166:167]
	v_pk_mul_f32 v[146:147], v[146:147], v[166:167]
	v_pk_mul_f32 v[148:149], v[148:149], v[166:167]
	v_pk_mul_f32 v[150:151], v[150:151], v[166:167]
	v_exp_f32_e32 v144, v144
	v_exp_f32_e32 v145, v145
	v_exp_f32_e32 v146, v146
	v_exp_f32_e32 v147, v147
	v_exp_f32_e32 v148, v148
	v_exp_f32_e32 v149, v149
	v_exp_f32_e32 v150, v150
	v_exp_f32_e32 v151, v151
	v_add_f32_e32 v144, 1.0, v144
	v_add_f32_e32 v145, 1.0, v145
	v_add_f32_e32 v146, 1.0, v146
	v_add_f32_e32 v147, 1.0, v147
	v_add_f32_e32 v148, 1.0, v148
	v_add_f32_e32 v149, 1.0, v149
	v_add_f32_e32 v150, 1.0, v150
	v_add_f32_e32 v151, 1.0, v151
	v_rcp_f32_e32 v144, v144
	v_rcp_f32_e32 v145, v145
	v_rcp_f32_e32 v146, v146
	v_rcp_f32_e32 v147, v147
	v_rcp_f32_e32 v148, v148
	v_rcp_f32_e32 v149, v149
	v_rcp_f32_e32 v150, v150
	v_rcp_f32_e32 v151, v151
	v_nop
	v_pk_mul_f32 v[68:69], v[68:69], v[144:145]
	v_pk_mul_f32 v[70:71], v[70:71], v[146:147]
	v_pk_mul_f32 v[64:65], v[64:65], v[148:149]
	v_pk_mul_f32 v[66:67], v[66:67], v[150:151]
	v_cvt_pk_bf16_f32 v68, v68, v69
; __device__ __forceinline__ unsigned cvt_pk_bf16(float lo, float hi) { unsigned r; asm volatile("v_cvt_pk_bf16_f32 %0, %1, %2" : "=v"(r) : "v"(lo), "v"(hi)); return r; }
; __device__ __forceinline__ float gelu_tanh(float x) { const float u = 0.7978845608028654f * (x + 0.044715f * x * x * x); return x * fast_rcp(1.0f + fast_exp2(-2.0f * LOG2E * u)); }
;     __device__ __forceinline__ void operator()(const f32x4 (&acc)[2][2][4][2], const Unit& u, int wr, int wc, int fr, int fq) const {
;     ...
;             for (int m = 0; m < 4; ++m) { const int row = row0 + ai * HALF + m * 16; bf16_t* rowp = O + (size_t)row * ldc + col0; const float rs = rsv[ai][m];
; #pragma unroll
;                 for (int bj = 0; bj < 2; ++bj) { f32x4 v0 = acc[ai][bj][m][0] * rs, v1 = acc[ai][bj][m][1] * rs;
;                     if (ACT == 1) {
; #pragma unroll
;                         for (int j = 0; j < 4; ++j) { v0[j] = gelu_tanh(v0[j]); v1[j] = gelu_tanh(v1[j]); } }
;                     u32x4 w; w.x = cvt_pk_bf16(v0[0], v0[1]); w.y = cvt_pk_bf16(v0[2], v0[3]); w.z = cvt_pk_bf16(v1[0], v1[1]); w.w = cvt_pk_bf16(v1[2], v1[3]);
;                     *(u32x4*)(rowp + bj * HALF) = w; } }
	v_cvt_pk_bf16_f32 v69, v70, v71
	v_cvt_pk_bf16_f32 v70, v64, v65
	v_cvt_pk_bf16_f32 v71, v66, v67
	global_store_dwordx4 v[142:143], v[68:71], off offset:256
	v_lshl_add_u64 v[142:143], v[142:143], 0, s[10:11]
	v_lshl_add_u64 v[142:143], v[142:143], 0, s[10:11]
	v_lshl_add_u64 v[142:143], v[142:143], 0, s[10:11]
	v_lshl_add_u64 v[142:143], v[142:143], 0, s[10:11]
	v_lshl_add_u64 v[142:143], v[142:143], 0, s[10:11]
	v_pk_mul_f32 v[60:61], v[60:61], v[162:163] op_sel_hi:[1,0]
	v_pk_mul_f32 v[62:63], v[62:63], v[162:163] op_sel_hi:[1,0]
	v_pk_mul_f32 v[56:57], v[56:57], v[162:163] op_sel_hi:[1,0]
	v_pk_mul_f32 v[58:59], v[58:59], v[162:163] op_sel_hi:[1,0]
	v_pk_mul_f32 v[144:145], v[60:61], s[98:99]
	v_pk_mul_f32 v[146:147], v[62:63], s[98:99]
	v_pk_mul_f32 v[148:149], v[56:57], s[98:99]
	v_pk_mul_f32 v[150:151], v[58:59], s[98:99]
	v_pk_mul_f32 v[144:145], v[60:61], v[144:145]
	v_pk_mul_f32 v[146:147], v[62:63], v[146:147]
	v_pk_mul_f32 v[148:149], v[56:57], v[148:149]
	v_pk_mul_f32 v[150:151], v[58:59], v[150:151]
	v_pk_fma_f32 v[144:145], v[60:61], v[144:145], v[60:61]
	v_pk_fma_f32 v[146:147], v[62:63], v[146:147], v[62:63]
	v_pk_fma_f32 v[148:149], v[56:57], v[148:149], v[56:57]
	v_pk_fma_f32 v[150:151], v[58:59], v[150:151], v[58:59]
	v_pk_mul_f32 v[144:145], v[144:145], s[100:101]
	v_pk_mul_f32 v[146:147], v[146:147], s[100:101]
	v_pk_mul_f32 v[148:149], v[148:149], s[100:101]
	v_pk_mul_f32 v[150:151], v[150:151], s[100:101]
	v_pk_mul_f32 v[144:145], v[144:145], v[166:167]
	v_pk_mul_f32 v[146:147], v[146:147], v[166:167]
	v_pk_mul_f32 v[148:149], v[148:149], v[166:167]
	v_pk_mul_f32 v[150:151], v[150:151], v[166:167]
	v_exp_f32_e32 v144, v144
	v_exp_f32_e32 v145, v145
	v_exp_f32_e32 v146, v146
	v_exp_f32_e32 v147, v147
	v_exp_f32_e32 v148, v148
	v_exp_f32_e32 v149, v149
	v_exp_f32_e32 v150, v150
	v_exp_f32_e32 v151, v151
	v_add_f32_e32 v144, 1.0, v144
	v_add_f32_e32 v145, 1.0, v145
	v_add_f32_e32 v146, 1.0, v146
	v_add_f32_e32 v147, 1.0, v147
	v_add_f32_e32 v148, 1.0, v148
	v_add_f32_e32 v149, 1.0, v149
	v_add_f32_e32 v150, 1.0, v150
	v_add_f32_e32 v151, 1.0, v151
	v_rcp_f32_e32 v144, v144
	v_rcp_f32_e32 v145, v145
	v_rcp_f32_e32 v146, v146
	v_rcp_f32_e32 v147, v147
	v_rcp_f32_e32 v148, v148
	v_rcp_f32_e32 v149, v149
	v_rcp_f32_e32 v150, v150
	v_rcp_f32_e32 v151, v151
	v_nop
	v_pk_mul_f32 v[60:61], v[60:61], v[144:145]
	v_pk_mul_f32 v[62:63], v[62:63], v[146:147]
	v_pk_mul_f32 v[56:57], v[56:57], v[148:149]
	v_pk_mul_f32 v[58:59], v[58:59], v[150:151]
	v_cvt_pk_bf16_f32 v60, v60, v61
	v_cvt_pk_bf16_f32 v61, v62, v63
	v_cvt_pk_bf16_f32 v62, v56, v57
	v_cvt_pk_bf16_f32 v63, v58, v59
	global_store_dwordx4 v[142:143], v[60:63], off
	v_pk_mul_f32 v[52:53], v[52:53], v[162:163] op_sel_hi:[1,0]
	v_pk_mul_f32 v[54:55], v[54:55], v[162:163] op_sel_hi:[1,0]
	v_pk_mul_f32 v[48:49], v[48:49], v[162:163] op_sel_hi:[1,0]
	v_pk_mul_f32 v[50:51], v[50:51], v[162:163] op_sel_hi:[1,0]
	v_pk_mul_f32 v[144:145], v[52:53], s[98:99]
	v_pk_mul_f32 v[146:147], v[54:55], s[98:99]
	v_pk_mul_f32 v[148:149], v[48:49], s[98:99]
	v_pk_mul_f32 v[150:151], v[50:51], s[98:99]
	v_pk_mul_f32 v[144:145], v[52:53], v[144:145]
	v_pk_mul_f32 v[146:147], v[54:55], v[146:147]
	v_pk_mul_f32 v[148:149], v[48:49], v[148:149]
	v_pk_mul_f32 v[150:151], v[50:51], v[150:151]
	v_pk_fma_f32 v[144:145], v[52:53], v[144:145], v[52:53]
	v_pk_fma_f32 v[146:147], v[54:55], v[146:147], v[54:55]
	v_pk_fma_f32 v[148:149], v[48:49], v[148:149], v[48:49]
	v_pk_fma_f32 v[150:151], v[50:51], v[150:151], v[50:51]
	v_pk_mul_f32 v[144:145], v[144:145], s[100:101]
	v_pk_mul_f32 v[146:147], v[146:147], s[100:101]
	v_pk_mul_f32 v[148:149], v[148:149], s[100:101]
	v_pk_mul_f32 v[150:151], v[150:151], s[100:101]
	v_pk_mul_f32 v[144:145], v[144:145], v[166:167]
	v_pk_mul_f32 v[146:147], v[146:147], v[166:167]
	v_pk_mul_f32 v[148:149], v[148:149], v[166:167]
	v_pk_mul_f32 v[150:151], v[150:151], v[166:167]
	v_exp_f32_e32 v144, v144
	v_exp_f32_e32 v145, v145
	v_exp_f32_e32 v146, v146
	v_exp_f32_e32 v147, v147
	v_exp_f32_e32 v148, v148
	v_exp_f32_e32 v149, v149
	v_exp_f32_e32 v150, v150
	v_exp_f32_e32 v151, v151
	v_add_f32_e32 v144, 1.0, v144
	v_add_f32_e32 v145, 1.0, v145
	v_add_f32_e32 v146, 1.0, v146
	v_add_f32_e32 v147, 1.0, v147
	v_add_f32_e32 v148, 1.0, v148
	v_add_f32_e32 v149, 1.0, v149
	v_add_f32_e32 v150, 1.0, v150
	v_add_f32_e32 v151, 1.0, v151
	v_rcp_f32_e32 v144, v144
	v_rcp_f32_e32 v145, v145
	v_rcp_f32_e32 v146, v146
	v_rcp_f32_e32 v147, v147
	v_rcp_f32_e32 v148, v148
	v_rcp_f32_e32 v149, v149
	v_rcp_f32_e32 v150, v150
	v_rcp_f32_e32 v151, v151
	v_nop
	v_pk_mul_f32 v[52:53], v[52:53], v[144:145]
	v_pk_mul_f32 v[54:55], v[54:55], v[146:147]
	v_pk_mul_f32 v[48:49], v[48:49], v[148:149]
	v_pk_mul_f32 v[50:51], v[50:51], v[150:151]
	v_cvt_pk_bf16_f32 v52, v52, v53
	v_cvt_pk_bf16_f32 v53, v54, v55
	v_cvt_pk_bf16_f32 v54, v48, v49
	v_cvt_pk_bf16_f32 v55, v50, v51
	global_store_dwordx4 v[142:143], v[52:55], off offset:256
	v_lshl_add_u64 v[142:143], v[142:143], 0, s[10:11]
	v_pk_mul_f32 v[44:45], v[44:45], v[162:163] op_sel:[0,1]
	v_pk_mul_f32 v[46:47], v[46:47], v[162:163] op_sel:[0,1]
	v_pk_mul_f32 v[40:41], v[40:41], v[162:163] op_sel:[0,1]
	v_pk_mul_f32 v[42:43], v[42:43], v[162:163] op_sel:[0,1]
	v_pk_mul_f32 v[144:145], v[44:45], s[98:99]
	v_pk_mul_f32 v[146:147], v[46:47], s[98:99]
	v_pk_mul_f32 v[148:149], v[40:41], s[98:99]
	v_pk_mul_f32 v[150:151], v[42:43], s[98:99]
	v_pk_mul_f32 v[144:145], v[44:45], v[144:145]
	v_pk_mul_f32 v[146:147], v[46:47], v[146:147]
	v_pk_mul_f32 v[148:149], v[40:41], v[148:149]
	v_pk_mul_f32 v[150:151], v[42:43], v[150:151]
	v_pk_fma_f32 v[144:145], v[44:45], v[144:145], v[44:45]
; __device__ __forceinline__ unsigned cvt_pk_bf16(float lo, float hi) { unsigned r; asm volatile("v_cvt_pk_bf16_f32 %0, %1, %2" : "=v"(r) : "v"(lo), "v"(hi)); return r; }
; __device__ __forceinline__ float gelu_tanh(float x) { const float u = 0.7978845608028654f * (x + 0.044715f * x * x * x); return x * fast_rcp(1.0f + fast_exp2(-2.0f * LOG2E * u)); }
;     __device__ __forceinline__ void operator()(const f32x4 (&acc)[2][2][4][2], const Unit& u, int wr, int wc, int fr, int fq) const {
;     ...
;             for (int m = 0; m < 4; ++m) { const int row = row0 + ai * HALF + m * 16; bf16_t* rowp = O + (size_t)row * ldc + col0; const float rs = rsv[ai][m];
; #pragma unroll
;                 for (int bj = 0; bj < 2; ++bj) { f32x4 v0 = acc[ai][bj][m][0] * rs, v1 = acc[ai][bj][m][1] * rs;
;                     if (ACT == 1) {
; #pragma unroll
;                         for (int j = 0; j < 4; ++j) { v0[j] = gelu_tanh(v0[j]); v1[j] = gelu_tanh(v1[j]); } }
;                     u32x4 w; w.x = cvt_pk_bf16(v0[0], v0[1]); w.y = cvt_pk_bf16(v0[2], v0[3]); w.z = cvt_pk_bf16(v1[0], v1[1]); w.w = cvt_pk_bf16(v1[2], v1[3]);
;                     *(u32x4*)(rowp + bj * HALF) = w; } }
	v_pk_fma_f32 v[146:147], v[46:47], v[146:147], v[46:47]
	v_pk_fma_f32 v[148:149], v[40:41], v[148:149], v[40:41]
	v_pk_fma_f32 v[150:151], v[42:43], v[150:151], v[42:43]
	v_pk_mul_f32 v[144:145], v[144:145], s[100:101]
	v_pk_mul_f32 v[146:147], v[146:147], s[100:101]
	v_pk_mul_f32 v[148:149], v[148:149], s[100:101]
	v_pk_mul_f32 v[150:151], v[150:151], s[100:101]
	v_pk_mul_f32 v[144:145], v[144:145], v[166:167]
	v_pk_mul_f32 v[146:147], v[146:147], v[166:167]
	v_pk_mul_f32 v[148:149], v[148:149], v[166:167]
	v_pk_mul_f32 v[150:151], v[150:151], v[166:167]
	v_exp_f32_e32 v144, v144
	v_exp_f32_e32 v145, v145
	v_exp_f32_e32 v146, v146
	v_exp_f32_e32 v147, v147
	v_exp_f32_e32 v148, v148
	v_exp_f32_e32 v149, v149
	v_exp_f32_e32 v150, v150
	v_exp_f32_e32 v151, v151
	v_add_f32_e32 v144, 1.0, v144
	v_add_f32_e32 v145, 1.0, v145
	v_add_f32_e32 v146, 1.0, v146
	v_add_f32_e32 v147, 1.0, v147
	v_add_f32_e32 v148, 1.0, v148
	v_add_f32_e32 v149, 1.0, v149
	v_add_f32_e32 v150, 1.0, v150
	v_add_f32_e32 v151, 1.0, v151
	v_rcp_f32_e32 v144, v144
	v_rcp_f32_e32 v145, v145
	v_rcp_f32_e32 v146, v146
	v_rcp_f32_e32 v147, v147
	v_rcp_f32_e32 v148, v148
	v_rcp_f32_e32 v149, v149
	v_rcp_f32_e32 v150, v150
	v_rcp_f32_e32 v151, v151
	v_nop
	v_pk_mul_f32 v[44:45], v[44:45], v[144:145]
	v_pk_mul_f32 v[46:47], v[46:47], v[146:147]
	v_pk_mul_f32 v[40:41], v[40:41], v[148:149]
	v_pk_mul_f32 v[42:43], v[42:43], v[150:151]
	v_cvt_pk_bf16_f32 v44, v44, v45
	v_cvt_pk_bf16_f32 v45, v46, v47
	v_cvt_pk_bf16_f32 v46, v40, v41
	v_cvt_pk_bf16_f32 v47, v42, v43
	global_store_dwordx4 v[142:143], v[44:47], off
	v_pk_mul_f32 v[36:37], v[36:37], v[162:163] op_sel:[0,1]
	v_pk_mul_f32 v[38:39], v[38:39], v[162:163] op_sel:[0,1]
	v_pk_mul_f32 v[32:33], v[32:33], v[162:163] op_sel:[0,1]
	v_pk_mul_f32 v[34:35], v[34:35], v[162:163] op_sel:[0,1]
	v_pk_mul_f32 v[144:145], v[36:37], s[98:99]
	v_pk_mul_f32 v[146:147], v[38:39], s[98:99]
	v_pk_mul_f32 v[148:149], v[32:33], s[98:99]
	v_pk_mul_f32 v[150:151], v[34:35], s[98:99]
	v_pk_mul_f32 v[144:145], v[36:37], v[144:145]
	v_pk_mul_f32 v[146:147], v[38:39], v[146:147]
	v_pk_mul_f32 v[148:149], v[32:33], v[148:149]
	v_pk_mul_f32 v[150:151], v[34:35], v[150:151]
	v_pk_fma_f32 v[144:145], v[36:37], v[144:145], v[36:37]
	v_pk_fma_f32 v[146:147], v[38:39], v[146:147], v[38:39]
	v_pk_fma_f32 v[148:149], v[32:33], v[148:149], v[32:33]
	v_pk_fma_f32 v[150:151], v[34:35], v[150:151], v[34:35]
	v_pk_mul_f32 v[144:145], v[144:145], s[100:101]
	v_pk_mul_f32 v[146:147], v[146:147], s[100:101]
	v_pk_mul_f32 v[148:149], v[148:149], s[100:101]
	v_pk_mul_f32 v[150:151], v[150:151], s[100:101]
	v_pk_mul_f32 v[144:145], v[144:145], v[166:167]
	v_pk_mul_f32 v[146:147], v[146:147], v[166:167]
	v_pk_mul_f32 v[148:149], v[148:149], v[166:167]
	v_pk_mul_f32 v[150:151], v[150:151], v[166:167]
	v_exp_f32_e32 v144, v144
	v_exp_f32_e32 v145, v145
	v_exp_f32_e32 v146, v146
	v_exp_f32_e32 v147, v147
	v_exp_f32_e32 v148, v148
	v_exp_f32_e32 v149, v149
	v_exp_f32_e32 v150, v150
	v_exp_f32_e32 v151, v151
	v_add_f32_e32 v144, 1.0, v144
	v_add_f32_e32 v145, 1.0, v145
	v_add_f32_e32 v146, 1.0, v146
	v_add_f32_e32 v147, 1.0, v147
	v_add_f32_e32 v148, 1.0, v148
	v_add_f32_e32 v149, 1.0, v149
	v_add_f32_e32 v150, 1.0, v150
	v_add_f32_e32 v151, 1.0, v151
	v_rcp_f32_e32 v144, v144
	v_rcp_f32_e32 v145, v145
	v_rcp_f32_e32 v146, v146
	v_rcp_f32_e32 v147, v147
	v_rcp_f32_e32 v148, v148
	v_rcp_f32_e32 v149, v149
	v_rcp_f32_e32 v150, v150
	v_rcp_f32_e32 v151, v151
	v_nop
	v_pk_mul_f32 v[36:37], v[36:37], v[144:145]
	v_pk_mul_f32 v[38:39], v[38:39], v[146:147]
	v_pk_mul_f32 v[32:33], v[32:33], v[148:149]
	v_pk_mul_f32 v[34:35], v[34:35], v[150:151]
	v_cvt_pk_bf16_f32 v36, v36, v37
	v_cvt_pk_bf16_f32 v37, v38, v39
	v_cvt_pk_bf16_f32 v38, v32, v33
	v_cvt_pk_bf16_f32 v39, v34, v35
	global_store_dwordx4 v[142:143], v[36:39], off offset:256
	v_lshl_add_u64 v[142:143], v[142:143], 0, s[10:11]
	v_pk_mul_f32 v[28:29], v[28:29], v[164:165] op_sel_hi:[1,0]
	v_pk_mul_f32 v[30:31], v[30:31], v[164:165] op_sel_hi:[1,0]
	v_pk_mul_f32 v[24:25], v[24:25], v[164:165] op_sel_hi:[1,0]
	v_pk_mul_f32 v[26:27], v[26:27], v[164:165] op_sel_hi:[1,0]
	v_pk_mul_f32 v[144:145], v[28:29], s[98:99]
	v_pk_mul_f32 v[146:147], v[30:31], s[98:99]
	v_pk_mul_f32 v[148:149], v[24:25], s[98:99]
	v_pk_mul_f32 v[150:151], v[26:27], s[98:99]
	v_pk_mul_f32 v[144:145], v[28:29], v[144:145]
	v_pk_mul_f32 v[146:147], v[30:31], v[146:147]
	v_pk_mul_f32 v[148:149], v[24:25], v[148:149]
	v_pk_mul_f32 v[150:151], v[26:27], v[150:151]
	v_pk_fma_f32 v[144:145], v[28:29], v[144:145], v[28:29]
	v_pk_fma_f32 v[146:147], v[30:31], v[146:147], v[30:31]
	v_pk_fma_f32 v[148:149], v[24:25], v[148:149], v[24:25]
	v_pk_fma_f32 v[150:151], v[26:27], v[150:151], v[26:27]
	v_pk_mul_f32 v[144:145], v[144:145], s[100:101]
	v_pk_mul_f32 v[146:147], v[146:147], s[100:101]
	v_pk_mul_f32 v[148:149], v[148:149], s[100:101]
	v_pk_mul_f32 v[150:151], v[150:151], s[100:101]
	v_pk_mul_f32 v[144:145], v[144:145], v[166:167]
	v_pk_mul_f32 v[146:147], v[146:147], v[166:167]
	v_pk_mul_f32 v[148:149], v[148:149], v[166:167]
	v_pk_mul_f32 v[150:151], v[150:151], v[166:167]
	v_exp_f32_e32 v144, v144
	v_exp_f32_e32 v145, v145
	v_exp_f32_e32 v146, v146
	v_exp_f32_e32 v147, v147
	v_exp_f32_e32 v148, v148
	v_exp_f32_e32 v149, v149
	v_exp_f32_e32 v150, v150
	v_exp_f32_e32 v151, v151
	v_add_f32_e32 v144, 1.0, v144
	v_add_f32_e32 v145, 1.0, v145
	v_add_f32_e32 v146, 1.0, v146
	v_add_f32_e32 v147, 1.0, v147
	v_add_f32_e32 v148, 1.0, v148
	v_add_f32_e32 v149, 1.0, v149
	v_add_f32_e32 v150, 1.0, v150
	v_add_f32_e32 v151, 1.0, v151
	v_rcp_f32_e32 v144, v144
	v_rcp_f32_e32 v145, v145
; __device__ __forceinline__ unsigned cvt_pk_bf16(float lo, float hi) { unsigned r; asm volatile("v_cvt_pk_bf16_f32 %0, %1, %2" : "=v"(r) : "v"(lo), "v"(hi)); return r; }
; __device__ __forceinline__ float gelu_tanh(float x) { const float u = 0.7978845608028654f * (x + 0.044715f * x * x * x); return x * fast_rcp(1.0f + fast_exp2(-2.0f * LOG2E * u)); }
;     __device__ __forceinline__ void operator()(const f32x4 (&acc)[2][2][4][2], const Unit& u, int wr, int wc, int fr, int fq) const {
;     ...
;             for (int m = 0; m < 4; ++m) { const int row = row0 + ai * HALF + m * 16; bf16_t* rowp = O + (size_t)row * ldc + col0; const float rs = rsv[ai][m];
; #pragma unroll
;                 for (int bj = 0; bj < 2; ++bj) { f32x4 v0 = acc[ai][bj][m][0] * rs, v1 = acc[ai][bj][m][1] * rs;
;                     if (ACT == 1) {
; #pragma unroll
;                         for (int j = 0; j < 4; ++j) { v0[j] = gelu_tanh(v0[j]); v1[j] = gelu_tanh(v1[j]); } }
;                     u32x4 w; w.x = cvt_pk_bf16(v0[0], v0[1]); w.y = cvt_pk_bf16(v0[2], v0[3]); w.z = cvt_pk_bf16(v1[0], v1[1]); w.w = cvt_pk_bf16(v1[2], v1[3]);
;                     *(u32x4*)(rowp + bj * HALF) = w; } }
	v_rcp_f32_e32 v146, v146
	v_rcp_f32_e32 v147, v147
	v_rcp_f32_e32 v148, v148
	v_rcp_f32_e32 v149, v149
	v_rcp_f32_e32 v150, v150
	v_rcp_f32_e32 v151, v151
	v_nop
	v_pk_mul_f32 v[28:29], v[28:29], v[144:145]
	v_pk_mul_f32 v[30:31], v[30:31], v[146:147]
	v_pk_mul_f32 v[24:25], v[24:25], v[148:149]
	v_pk_mul_f32 v[26:27], v[26:27], v[150:151]
	v_cvt_pk_bf16_f32 v28, v28, v29
	v_cvt_pk_bf16_f32 v29, v30, v31
	v_cvt_pk_bf16_f32 v30, v24, v25
	v_cvt_pk_bf16_f32 v31, v26, v27
	global_store_dwordx4 v[142:143], v[28:31], off
	v_pk_mul_f32 v[20:21], v[20:21], v[164:165] op_sel_hi:[1,0]
	v_pk_mul_f32 v[22:23], v[22:23], v[164:165] op_sel_hi:[1,0]
	v_pk_mul_f32 v[16:17], v[16:17], v[164:165] op_sel_hi:[1,0]
	v_pk_mul_f32 v[18:19], v[18:19], v[164:165] op_sel_hi:[1,0]
	v_pk_mul_f32 v[144:145], v[20:21], s[98:99]
	v_pk_mul_f32 v[146:147], v[22:23], s[98:99]
	v_pk_mul_f32 v[148:149], v[16:17], s[98:99]
	v_pk_mul_f32 v[150:151], v[18:19], s[98:99]
	v_pk_mul_f32 v[144:145], v[20:21], v[144:145]
	v_pk_mul_f32 v[146:147], v[22:23], v[146:147]
	v_pk_mul_f32 v[148:149], v[16:17], v[148:149]
	v_pk_mul_f32 v[150:151], v[18:19], v[150:151]
	v_pk_fma_f32 v[144:145], v[20:21], v[144:145], v[20:21]
	v_pk_fma_f32 v[146:147], v[22:23], v[146:147], v[22:23]
	v_pk_fma_f32 v[148:149], v[16:17], v[148:149], v[16:17]
	v_pk_fma_f32 v[150:151], v[18:19], v[150:151], v[18:19]
	v_pk_mul_f32 v[144:145], v[144:145], s[100:101]
	v_pk_mul_f32 v[146:147], v[146:147], s[100:101]
	v_pk_mul_f32 v[148:149], v[148:149], s[100:101]
	v_pk_mul_f32 v[150:151], v[150:151], s[100:101]
	v_pk_mul_f32 v[144:145], v[144:145], v[166:167]
	v_pk_mul_f32 v[146:147], v[146:147], v[166:167]
	v_pk_mul_f32 v[148:149], v[148:149], v[166:167]
	v_pk_mul_f32 v[150:151], v[150:151], v[166:167]
	v_exp_f32_e32 v144, v144
	v_exp_f32_e32 v145, v145
	v_exp_f32_e32 v146, v146
	v_exp_f32_e32 v147, v147
	v_exp_f32_e32 v148, v148
	v_exp_f32_e32 v149, v149
	v_exp_f32_e32 v150, v150
	v_exp_f32_e32 v151, v151
	v_add_f32_e32 v144, 1.0, v144
	v_add_f32_e32 v145, 1.0, v145
	v_add_f32_e32 v146, 1.0, v146
	v_add_f32_e32 v147, 1.0, v147
	v_add_f32_e32 v148, 1.0, v148
	v_add_f32_e32 v149, 1.0, v149
	v_add_f32_e32 v150, 1.0, v150
	v_add_f32_e32 v151, 1.0, v151
	v_rcp_f32_e32 v144, v144
	v_rcp_f32_e32 v145, v145
	v_rcp_f32_e32 v146, v146
	v_rcp_f32_e32 v147, v147
	v_rcp_f32_e32 v148, v148
	v_rcp_f32_e32 v149, v149
	v_rcp_f32_e32 v150, v150
	v_rcp_f32_e32 v151, v151
	v_nop
	v_pk_mul_f32 v[20:21], v[20:21], v[144:145]
	v_pk_mul_f32 v[22:23], v[22:23], v[146:147]
	v_pk_mul_f32 v[16:17], v[16:17], v[148:149]
	v_pk_mul_f32 v[18:19], v[18:19], v[150:151]
	v_cvt_pk_bf16_f32 v20, v20, v21
	v_cvt_pk_bf16_f32 v21, v22, v23
	v_cvt_pk_bf16_f32 v22, v16, v17
	v_cvt_pk_bf16_f32 v23, v18, v19
	global_store_dwordx4 v[142:143], v[20:23], off offset:256
	v_lshl_add_u64 v[142:143], v[142:143], 0, s[10:11]
	v_pk_mul_f32 v[12:13], v[12:13], v[164:165] op_sel:[0,1]
	v_pk_mul_f32 v[14:15], v[14:15], v[164:165] op_sel:[0,1]
	v_pk_mul_f32 v[8:9], v[8:9], v[164:165] op_sel:[0,1]
	v_pk_mul_f32 v[10:11], v[10:11], v[164:165] op_sel:[0,1]
	v_pk_mul_f32 v[144:145], v[12:13], s[98:99]
	v_pk_mul_f32 v[146:147], v[14:15], s[98:99]
	v_pk_mul_f32 v[148:149], v[8:9], s[98:99]
	v_pk_mul_f32 v[150:151], v[10:11], s[98:99]
	v_pk_mul_f32 v[144:145], v[12:13], v[144:145]
	v_pk_mul_f32 v[146:147], v[14:15], v[146:147]
	v_pk_mul_f32 v[148:149], v[8:9], v[148:149]
	v_pk_mul_f32 v[150:151], v[10:11], v[150:151]
	v_pk_fma_f32 v[144:145], v[12:13], v[144:145], v[12:13]
	v_pk_fma_f32 v[146:147], v[14:15], v[146:147], v[14:15]
	v_pk_fma_f32 v[148:149], v[8:9], v[148:149], v[8:9]
	v_pk_fma_f32 v[150:151], v[10:11], v[150:151], v[10:11]
	v_pk_mul_f32 v[144:145], v[144:145], s[100:101]
; __device__ __forceinline__ unsigned cvt_pk_bf16(float lo, float hi) { unsigned r; asm volatile("v_cvt_pk_bf16_f32 %0, %1, %2" : "=v"(r) : "v"(lo), "v"(hi)); return r; }
; __device__ __forceinline__ float gelu_tanh(float x) { const float u = 0.7978845608028654f * (x + 0.044715f * x * x * x); return x * fast_rcp(1.0f + fast_exp2(-2.0f * LOG2E * u)); }
; #define PG8_BAR __builtin_amdgcn_s_barrier()
;     __device__ __forceinline__ void operator()(const f32x4 (&acc)[2][2][4][2], const Unit& u, int wr, int wc, int fr, int fq) const {
;     ...
;             for (int m = 0; m < 4; ++m) { const int row = row0 + ai * HALF + m * 16; bf16_t* rowp = O + (size_t)row * ldc + col0; const float rs = rsv[ai][m];
; #pragma unroll
;                 for (int bj = 0; bj < 2; ++bj) { f32x4 v0 = acc[ai][bj][m][0] * rs, v1 = acc[ai][bj][m][1] * rs;
;                     if (ACT == 1) {
; #pragma unroll
;                         for (int j = 0; j < 4; ++j) { v0[j] = gelu_tanh(v0[j]); v1[j] = gelu_tanh(v1[j]); } }
;                     u32x4 w; w.x = cvt_pk_bf16(v0[0], v0[1]); w.y = cvt_pk_bf16(v0[2], v0[3]); w.z = cvt_pk_bf16(v1[0], v1[1]); w.w = cvt_pk_bf16(v1[2], v1[3]);
;                     *(u32x4*)(rowp + bj * HALF) = w; } }
; template <class Epi, bool ALIGN_EPI>
; __device__ __forceinline__ void gemm_phase(LAS unsigned char* lds, const Gemm g, const StaticOrder& S, const Epi& E, const int tid) {
;     ...
;         if (!has_next) break;
; #pragma unroll
;         for (int a = 0; a < 2; ++a)
; #pragma unroll
;             for (int b = 0; b < 2; ++b)
; #pragma unroll
;                 for (int m = 0; m < 4; ++m)
; #pragma unroll
;                     for (int n = 0; n < 2; ++n) acc[a][b][m][n] = (f32x4){0.f, 0.f, 0.f, 0.f};
;         cur = nxt; cA = nA; cB = nB; ++ui;
;         if constexpr (ALIGN_EPI) { if (wr == 1) PG8_BAR; }
	v_pk_mul_f32 v[146:147], v[146:147], s[100:101]
	v_pk_mul_f32 v[148:149], v[148:149], s[100:101]
	v_pk_mul_f32 v[150:151], v[150:151], s[100:101]
	v_pk_mul_f32 v[144:145], v[144:145], v[166:167]
	v_pk_mul_f32 v[146:147], v[146:147], v[166:167]
	v_pk_mul_f32 v[148:149], v[148:149], v[166:167]
	v_pk_mul_f32 v[150:151], v[150:151], v[166:167]
	v_exp_f32_e32 v144, v144
	v_exp_f32_e32 v145, v145
	v_exp_f32_e32 v146, v146
	v_exp_f32_e32 v147, v147
	v_exp_f32_e32 v148, v148
	v_exp_f32_e32 v149, v149
	v_exp_f32_e32 v150, v150
	v_exp_f32_e32 v151, v151
	v_add_f32_e32 v144, 1.0, v144
	v_add_f32_e32 v145, 1.0, v145
	v_add_f32_e32 v146, 1.0, v146
	v_add_f32_e32 v147, 1.0, v147
	v_add_f32_e32 v148, 1.0, v148
	v_add_f32_e32 v149, 1.0, v149
	v_add_f32_e32 v150, 1.0, v150
	v_add_f32_e32 v151, 1.0, v151
	v_rcp_f32_e32 v144, v144
	v_rcp_f32_e32 v145, v145
	v_rcp_f32_e32 v146, v146
	v_rcp_f32_e32 v147, v147
	v_rcp_f32_e32 v148, v148
	v_rcp_f32_e32 v149, v149
	v_rcp_f32_e32 v150, v150
	v_rcp_f32_e32 v151, v151
	v_nop
	v_pk_mul_f32 v[12:13], v[12:13], v[144:145]
	v_pk_mul_f32 v[14:15], v[14:15], v[146:147]
	v_pk_mul_f32 v[8:9], v[8:9], v[148:149]
	v_pk_mul_f32 v[10:11], v[10:11], v[150:151]
	v_cvt_pk_bf16_f32 v12, v12, v13
	v_cvt_pk_bf16_f32 v13, v14, v15
	v_cvt_pk_bf16_f32 v14, v8, v9
	v_cvt_pk_bf16_f32 v15, v10, v11
	global_store_dwordx4 v[142:143], v[12:15], off
	v_pk_mul_f32 v[4:5], v[4:5], v[164:165] op_sel:[0,1]
	v_pk_mul_f32 v[6:7], v[6:7], v[164:165] op_sel:[0,1]
	v_pk_mul_f32 v[0:1], v[0:1], v[164:165] op_sel:[0,1]
	v_pk_mul_f32 v[2:3], v[2:3], v[164:165] op_sel:[0,1]
	v_pk_mul_f32 v[144:145], v[4:5], s[98:99]
	v_pk_mul_f32 v[146:147], v[6:7], s[98:99]
	v_pk_mul_f32 v[148:149], v[0:1], s[98:99]
	v_pk_mul_f32 v[150:151], v[2:3], s[98:99]
	v_pk_mul_f32 v[144:145], v[4:5], v[144:145]
	v_pk_mul_f32 v[146:147], v[6:7], v[146:147]
	v_pk_mul_f32 v[148:149], v[0:1], v[148:149]
	v_pk_mul_f32 v[150:151], v[2:3], v[150:151]
	v_pk_fma_f32 v[144:145], v[4:5], v[144:145], v[4:5]
	v_pk_fma_f32 v[146:147], v[6:7], v[146:147], v[6:7]
	v_pk_fma_f32 v[148:149], v[0:1], v[148:149], v[0:1]
	v_pk_fma_f32 v[150:151], v[2:3], v[150:151], v[2:3]
	v_pk_mul_f32 v[144:145], v[144:145], s[100:101]
	v_pk_mul_f32 v[146:147], v[146:147], s[100:101]
	v_pk_mul_f32 v[148:149], v[148:149], s[100:101]
	v_pk_mul_f32 v[150:151], v[150:151], s[100:101]
	v_pk_mul_f32 v[144:145], v[144:145], v[166:167]
	v_pk_mul_f32 v[146:147], v[146:147], v[166:167]
	v_pk_mul_f32 v[148:149], v[148:149], v[166:167]
	v_pk_mul_f32 v[150:151], v[150:151], v[166:167]
	v_exp_f32_e32 v144, v144
	v_exp_f32_e32 v145, v145
	v_exp_f32_e32 v146, v146
	v_exp_f32_e32 v147, v147
	v_exp_f32_e32 v148, v148
	v_exp_f32_e32 v149, v149
	v_exp_f32_e32 v150, v150
	v_exp_f32_e32 v151, v151
	v_add_f32_e32 v144, 1.0, v144
	v_add_f32_e32 v145, 1.0, v145
	v_add_f32_e32 v146, 1.0, v146
	v_add_f32_e32 v147, 1.0, v147
	v_add_f32_e32 v148, 1.0, v148
	v_add_f32_e32 v149, 1.0, v149
	v_add_f32_e32 v150, 1.0, v150
	v_add_f32_e32 v151, 1.0, v151
	v_rcp_f32_e32 v144, v144
	v_rcp_f32_e32 v145, v145
	v_rcp_f32_e32 v146, v146
	v_rcp_f32_e32 v147, v147
	v_rcp_f32_e32 v148, v148
	v_rcp_f32_e32 v149, v149
	v_rcp_f32_e32 v150, v150
	v_rcp_f32_e32 v151, v151
	v_nop
	v_pk_mul_f32 v[4:5], v[4:5], v[144:145]
	v_pk_mul_f32 v[6:7], v[6:7], v[146:147]
	v_pk_mul_f32 v[0:1], v[0:1], v[148:149]
	v_pk_mul_f32 v[2:3], v[2:3], v[150:151]
	v_cvt_pk_bf16_f32 v4, v4, v5
	v_cvt_pk_bf16_f32 v5, v6, v7
	v_cvt_pk_bf16_f32 v6, v0, v1
	v_cvt_pk_bf16_f32 v7, v2, v3
	global_store_dwordx4 v[142:143], v[4:7], off offset:256
	s_mov_b64 s[10:11], -1
	s_and_b64 vcc, exec, s[8:9]
	s_cbranch_vccnz .LBB0_322
	s_andn2_b64 vcc, exec, s[40:41]
	s_cbranch_vccnz .LBB0_321
	s_barrier
	s_branch .LBB0_321
